# transposed K/V staging in mc_item<2> and ma_ret: lane pairs exchange halves (DPP + v_perm) and store one dword instead of two 16-bit LDS writes
# speedup vs baseline: 1.0049x; 1.0049x over previous
; #define LAS __attribute__((address_space(3)))
; __device__ __forceinline__ f32x4 mma16(bf16x8 a, bf16x8 b, f32x4 c) { return __builtin_amdgcn_mfma_f32_16x16x32_bf16(a, b, c, 0, 0, 0); }
; template <int F> __device__ __forceinline__ void st_T(ldsp dst, int dp_unused, const u32x4 (&r)[F / 64], int wave, int lane) {
;     ldsp base = dst + (size_t)((2 * (wave >> 1) + (lane >> 5)) * 8 * 72 + 32 * (wave & 1) + (lane & 31)) * 2;
; #pragma unroll
;     for (int it = 0; it < F / 64; ++it) { const u32x4 w = r[it];
; #pragma unroll
;         for (int i = 0; i < 4; ++i) {
;             *(LAS bf16_t*)(base + (64 * it + 2 * i) * 144) = (bf16_t)(w[i] & 0xffffu);
;             *(LAS bf16_t*)(base + (64 * it + 2 * i + 1) * 144) = (bf16_t)(w[i] >> 16); } }
; }
; __device__ __forceinline__ void ma_ret_item(const Params& p, ldsp lds, int item) {
;     ...
;     for (int j = 0; j < 4; ++j) { const size_t rowj = (size_t)b * 2048 + (sc * 4 + j) * 64;
;         st_T<256>(KTt, 72, kr, wave, lane); st_T<128>(VTt, 72, vr, wave, lane);
;         __syncthreads();
;         if (j < 3) { const size_t rown = rowj + 64; ld_T<256>(kr, Pb + rown * NO + O_K + h * 256, NO, wave, lane); ld_T<128>(vr, Pb + rown * NO + O_V + h * 512 + es * 128, NO, wave, lane); }
; #pragma unroll
;         for (int ks = 0; ks < 2; ++ks) { const bf16x8 bf = ldfrag(VTt, (16 * wave + l15) * 72 + 32 * ks + 8 * q4);
; #pragma unroll
;             for (int i = 0; i < 16; ++i) acc[i] = mma16(ldfrag(KTt, (16 * i + l15) * 72 + 32 * ks + 8 * q4), bf, acc[i]); }
;         __syncthreads(); }
.LBB0_678:
	s_waitcnt vmcnt(5)
	v_and_b32_e32 v134, 1, v161
	v_sub_u32_e32 v135, 0, v134
	v_mov_b32_e32 v136, 0x5040100
	v_mov_b32_e32 v138, 0x3020706
	v_bfi_b32 v140, v135, v138, v136
	v_mul_u32_u24_e32 v141, 0x8e, v134
	v_add_u32_e32 v141, v141, v100
	v_mov_b32_dpp v142, v22 quad_perm:[1,0,3,2] row_mask:0xf bank_mask:0xf
	v_perm_b32 v143, v142, v22, v140
	ds_write_b32 v141, v143
	v_mov_b32_dpp v144, v23 quad_perm:[1,0,3,2] row_mask:0xf bank_mask:0xf
	v_perm_b32 v145, v144, v23, v140
	ds_write_b32 v141, v145 offset:288
	v_mov_b32_dpp v146, v24 quad_perm:[1,0,3,2] row_mask:0xf bank_mask:0xf
	v_perm_b32 v147, v146, v24, v140
	ds_write_b32 v141, v147 offset:576
	v_mov_b32_dpp v148, v25 quad_perm:[1,0,3,2] row_mask:0xf bank_mask:0xf
	v_perm_b32 v149, v148, v25, v140
	ds_write_b32 v141, v149 offset:864
	s_waitcnt vmcnt(4)
	v_mov_b32_dpp v142, v18 quad_perm:[1,0,3,2] row_mask:0xf bank_mask:0xf
	v_perm_b32 v143, v142, v18, v140
	ds_write_b32 v141, v143 offset:9216
	v_mov_b32_dpp v144, v19 quad_perm:[1,0,3,2] row_mask:0xf bank_mask:0xf
	v_perm_b32 v145, v144, v19, v140
	ds_write_b32 v141, v145 offset:9504
	v_mov_b32_dpp v146, v20 quad_perm:[1,0,3,2] row_mask:0xf bank_mask:0xf
	v_perm_b32 v147, v146, v20, v140
	ds_write_b32 v141, v147 offset:9792
	v_mov_b32_dpp v148, v21 quad_perm:[1,0,3,2] row_mask:0xf bank_mask:0xf
	v_perm_b32 v149, v148, v21, v140
	ds_write_b32 v141, v149 offset:10080
	s_waitcnt vmcnt(3)
	v_mov_b32_dpp v142, v12 quad_perm:[1,0,3,2] row_mask:0xf bank_mask:0xf
	v_perm_b32 v143, v142, v12, v140
	ds_write_b32 v141, v143 offset:18432
	v_mov_b32_dpp v144, v13 quad_perm:[1,0,3,2] row_mask:0xf bank_mask:0xf
	v_perm_b32 v145, v144, v13, v140
	ds_write_b32 v141, v145 offset:18720
	v_mov_b32_dpp v146, v14 quad_perm:[1,0,3,2] row_mask:0xf bank_mask:0xf
	v_perm_b32 v147, v146, v14, v140
	ds_write_b32 v141, v147 offset:19008
	v_mov_b32_dpp v148, v15 quad_perm:[1,0,3,2] row_mask:0xf bank_mask:0xf
	v_perm_b32 v149, v148, v15, v140
	ds_write_b32 v141, v149 offset:19296
	s_waitcnt vmcnt(2)
	v_mov_b32_dpp v142, v4 quad_perm:[1,0,3,2] row_mask:0xf bank_mask:0xf
	v_perm_b32 v143, v142, v4, v140
	ds_write_b32 v141, v143 offset:27648
	v_mov_b32_dpp v144, v5 quad_perm:[1,0,3,2] row_mask:0xf bank_mask:0xf
	v_perm_b32 v145, v144, v5, v140
	ds_write_b32 v141, v145 offset:27936
	v_mov_b32_dpp v146, v6 quad_perm:[1,0,3,2] row_mask:0xf bank_mask:0xf
	v_perm_b32 v147, v146, v6, v140
	ds_write_b32 v141, v147 offset:28224
	v_mov_b32_dpp v148, v7 quad_perm:[1,0,3,2] row_mask:0xf bank_mask:0xf
	v_perm_b32 v149, v148, v7, v140
	ds_write_b32 v141, v149 offset:28512
	s_waitcnt vmcnt(1)
	v_mov_b32_dpp v142, v8 quad_perm:[1,0,3,2] row_mask:0xf bank_mask:0xf
	v_perm_b32 v143, v142, v8, v140
	ds_write_b32 v141, v143 offset:36864
	v_mov_b32_dpp v144, v9 quad_perm:[1,0,3,2] row_mask:0xf bank_mask:0xf
	v_perm_b32 v145, v144, v9, v140
	ds_write_b32 v141, v145 offset:37152
	v_mov_b32_dpp v146, v10 quad_perm:[1,0,3,2] row_mask:0xf bank_mask:0xf
	v_perm_b32 v147, v146, v10, v140
	ds_write_b32 v141, v147 offset:37440
	v_mov_b32_dpp v148, v11 quad_perm:[1,0,3,2] row_mask:0xf bank_mask:0xf
	v_perm_b32 v149, v148, v11, v140
	ds_write_b32 v141, v149 offset:37728
	s_waitcnt vmcnt(0)
	v_mov_b32_dpp v142, v0 quad_perm:[1,0,3,2] row_mask:0xf bank_mask:0xf
	v_perm_b32 v143, v142, v0, v140
	ds_write_b32 v141, v143 offset:46080
	v_mov_b32_dpp v144, v1 quad_perm:[1,0,3,2] row_mask:0xf bank_mask:0xf
	v_perm_b32 v145, v144, v1, v140
	ds_write_b32 v141, v145 offset:46368
	v_mov_b32_dpp v146, v2 quad_perm:[1,0,3,2] row_mask:0xf bank_mask:0xf
	v_perm_b32 v147, v146, v2, v140
	ds_write_b32 v141, v147 offset:46656
	v_mov_b32_dpp v148, v3 quad_perm:[1,0,3,2] row_mask:0xf bank_mask:0xf
	v_perm_b32 v149, v148, v3, v140
	ds_write_b32 v141, v149 offset:46944
	v_lshl_add_u64 v[0:1], v[98:99], 0, s[10:11]
	s_waitcnt lgkmcnt(0)
	s_barrier
	global_load_dwordx4 v[22:25], v[0:1], off offset:-256
	global_load_dwordx4 v[18:21], v[0:1], off offset:-128
	global_load_dwordx4 v[12:15], v[0:1], off
	global_load_dwordx4 v[4:7], v[0:1], off offset:128
	v_lshl_add_u64 v[0:1], v[96:97], 0, s[10:11]
	v_add_co_u32_e32 v0, vcc, s54, v0
	s_add_u32 s10, s10, 0xc0000
	s_nop 0
	v_addc_co_u32_e32 v1, vcc, 0, v1, vcc
	global_load_dwordx4 v[8:11], v[0:1], off
	s_nop 0
	global_load_dwordx4 v[0:3], v[0:1], off offset:128
	ds_read_b128 v[90:93], v130 offset:36864
	ds_read_b128 v[242:245], v130 offset:36928
	ds_read_b128 v[210:213], v132
	ds_read_b128 v[214:217], v131
	ds_read_b128 v[218:221], v129
	ds_read_b128 v[222:225], v128
	ds_read_b128 v[226:229], v127
	ds_read_b128 v[230:233], v126
	ds_read_b128 v[234:237], v125
	ds_read_b128 v[238:241], v124
	s_addc_u32 s11, s11, 0
	s_cmp_lg_u32 s10, 0x240000
	s_waitcnt lgkmcnt(7)
	v_mfma_f32_16x16x32_bf16 v[26:29], v[210:213], v[90:93], v[26:29]
	ds_read_b128 v[210:213], v123
	s_waitcnt lgkmcnt(7)
	v_mfma_f32_16x16x32_bf16 v[34:37], v[214:217], v[90:93], v[34:37]
	ds_read_b128 v[214:217], v122
	s_waitcnt lgkmcnt(7)
	v_mfma_f32_16x16x32_bf16 v[38:41], v[218:221], v[90:93], v[38:41]
	ds_read_b128 v[218:221], v121
	s_waitcnt lgkmcnt(7)
	v_mfma_f32_16x16x32_bf16 v[42:45], v[222:225], v[90:93], v[42:45]
	ds_read_b128 v[222:225], v120
	s_waitcnt lgkmcnt(7)
	v_mfma_f32_16x16x32_bf16 v[46:49], v[226:229], v[90:93], v[46:49]
	ds_read_b128 v[226:229], v119
	s_waitcnt lgkmcnt(7)
	v_mfma_f32_16x16x32_bf16 v[50:53], v[230:233], v[90:93], v[50:53]
	ds_read_b128 v[230:233], v118
	s_waitcnt lgkmcnt(7)
	v_mfma_f32_16x16x32_bf16 v[54:57], v[234:237], v[90:93], v[54:57]
	ds_read_b128 v[234:237], v117
	s_waitcnt lgkmcnt(7)
	v_mfma_f32_16x16x32_bf16 v[58:61], v[238:241], v[90:93], v[58:61]
	ds_read_b128 v[238:241], v116
	s_waitcnt lgkmcnt(7)
; #define LAS __attribute__((address_space(3)))
; __device__ __forceinline__ f32x4 mma16(bf16x8 a, bf16x8 b, f32x4 c) { return __builtin_amdgcn_mfma_f32_16x16x32_bf16(a, b, c, 0, 0, 0); }
; template <int F> __device__ __forceinline__ void st_T(ldsp dst, int dp_unused, const u32x4 (&r)[F / 64], int wave, int lane) {
;     ldsp base = dst + (size_t)((2 * (wave >> 1) + (lane >> 5)) * 8 * 72 + 32 * (wave & 1) + (lane & 31)) * 2;
; #pragma unroll
;     for (int it = 0; it < F / 64; ++it) { const u32x4 w = r[it];
; #pragma unroll
;         for (int i = 0; i < 4; ++i) {
;             *(LAS bf16_t*)(base + (64 * it + 2 * i) * 144) = (bf16_t)(w[i] & 0xffffu);
;             *(LAS bf16_t*)(base + (64 * it + 2 * i + 1) * 144) = (bf16_t)(w[i] >> 16); } }
; }
; __device__ __forceinline__ void ma_ret_item(const Params& p, ldsp lds, int item) {
;     ...
; #pragma unroll
;         for (int ks = 0; ks < 2; ++ks) { const bf16x8 bf = ldfrag(VTt, (16 * wave + l15) * 72 + 32 * ks + 8 * q4);
; #pragma unroll
;             for (int i = 0; i < 16; ++i) acc[i] = mma16(ldfrag(KTt, (16 * i + l15) * 72 + 32 * ks + 8 * q4), bf, acc[i]); }
;         __syncthreads(); }
	v_mfma_f32_16x16x32_bf16 v[62:65], v[210:213], v[90:93], v[62:65]
	ds_read_b128 v[210:213], v115
	s_waitcnt lgkmcnt(7)
	v_mfma_f32_16x16x32_bf16 v[66:69], v[214:217], v[90:93], v[66:69]
	ds_read_b128 v[214:217], v114
	s_waitcnt lgkmcnt(7)
	v_mfma_f32_16x16x32_bf16 v[70:73], v[218:221], v[90:93], v[70:73]
	ds_read_b128 v[218:221], v113
	s_waitcnt lgkmcnt(7)
	v_mfma_f32_16x16x32_bf16 v[74:77], v[222:225], v[90:93], v[74:77]
	ds_read_b128 v[222:225], v112
	s_waitcnt lgkmcnt(7)
	v_mfma_f32_16x16x32_bf16 v[78:81], v[226:229], v[90:93], v[78:81]
	ds_read_b128 v[226:229], v111
	s_waitcnt lgkmcnt(7)
	v_mfma_f32_16x16x32_bf16 v[82:85], v[230:233], v[90:93], v[82:85]
	ds_read_b128 v[230:233], v110
	s_waitcnt lgkmcnt(7)
	v_mfma_f32_16x16x32_bf16 v[86:89], v[234:237], v[90:93], v[86:89]
	ds_read_b128 v[234:237], v109
	s_waitcnt lgkmcnt(7)
	v_mfma_f32_16x16x32_bf16 v[30:33], v[238:241], v[90:93], v[30:33]
	ds_read_b128 v[238:241], v108
	s_waitcnt lgkmcnt(7)
	v_mfma_f32_16x16x32_bf16 v[26:29], v[210:213], v[242:245], v[26:29]
	ds_read_b128 v[210:213], v107
	s_waitcnt lgkmcnt(7)
	v_mfma_f32_16x16x32_bf16 v[34:37], v[214:217], v[242:245], v[34:37]
	ds_read_b128 v[214:217], v106
	s_waitcnt lgkmcnt(7)
	v_mfma_f32_16x16x32_bf16 v[38:41], v[218:221], v[242:245], v[38:41]
	ds_read_b128 v[218:221], v105
	s_waitcnt lgkmcnt(7)
	v_mfma_f32_16x16x32_bf16 v[42:45], v[222:225], v[242:245], v[42:45]
	ds_read_b128 v[222:225], v104
	s_waitcnt lgkmcnt(7)
	v_mfma_f32_16x16x32_bf16 v[46:49], v[226:229], v[242:245], v[46:49]
	ds_read_b128 v[226:229], v103
	s_waitcnt lgkmcnt(7)
	v_mfma_f32_16x16x32_bf16 v[50:53], v[230:233], v[242:245], v[50:53]
	ds_read_b128 v[230:233], v102
	s_waitcnt lgkmcnt(7)
	v_mfma_f32_16x16x32_bf16 v[54:57], v[234:237], v[242:245], v[54:57]
	ds_read_b128 v[234:237], v101
	s_waitcnt lgkmcnt(7)
	v_mfma_f32_16x16x32_bf16 v[58:61], v[238:241], v[242:245], v[58:61]
	ds_read_b128 v[238:241], v16
	s_waitcnt lgkmcnt(7)
	v_mfma_f32_16x16x32_bf16 v[62:65], v[210:213], v[242:245], v[62:65]
	s_waitcnt lgkmcnt(6)
	v_mfma_f32_16x16x32_bf16 v[66:69], v[214:217], v[242:245], v[66:69]
	s_waitcnt lgkmcnt(5)
	v_mfma_f32_16x16x32_bf16 v[70:73], v[218:221], v[242:245], v[70:73]
	s_waitcnt lgkmcnt(4)
	v_mfma_f32_16x16x32_bf16 v[74:77], v[222:225], v[242:245], v[74:77]
	s_waitcnt lgkmcnt(3)
	v_mfma_f32_16x16x32_bf16 v[78:81], v[226:229], v[242:245], v[78:81]
	s_waitcnt lgkmcnt(2)
	v_mfma_f32_16x16x32_bf16 v[82:85], v[230:233], v[242:245], v[82:85]
	s_waitcnt lgkmcnt(1)
	v_mfma_f32_16x16x32_bf16 v[86:89], v[234:237], v[242:245], v[86:89]
	s_waitcnt lgkmcnt(0)
	s_barrier
	v_mfma_f32_16x16x32_bf16 v[30:33], v[238:241], v[242:245], v[30:33]
	s_cbranch_scc1 .LBB0_678
	s_waitcnt vmcnt(5)
	v_and_b32_e32 v134, 1, v161
	v_sub_u32_e32 v135, 0, v134
	v_mov_b32_e32 v136, 0x5040100
	v_mov_b32_e32 v138, 0x3020706
	v_bfi_b32 v140, v135, v138, v136
	v_mul_u32_u24_e32 v141, 0x8e, v134
	v_add_u32_e32 v141, v141, v100
	v_mov_b32_dpp v142, v22 quad_perm:[1,0,3,2] row_mask:0xf bank_mask:0xf
	v_perm_b32 v143, v142, v22, v140
	ds_write_b32 v141, v143
	v_mov_b32_dpp v144, v23 quad_perm:[1,0,3,2] row_mask:0xf bank_mask:0xf
	v_perm_b32 v145, v144, v23, v140
	ds_write_b32 v141, v145 offset:288
	v_mov_b32_dpp v146, v24 quad_perm:[1,0,3,2] row_mask:0xf bank_mask:0xf
	v_perm_b32 v147, v146, v24, v140
	ds_write_b32 v141, v147 offset:576
	v_mov_b32_dpp v148, v25 quad_perm:[1,0,3,2] row_mask:0xf bank_mask:0xf
	v_perm_b32 v149, v148, v25, v140
	ds_write_b32 v141, v149 offset:864
	s_waitcnt vmcnt(4)
	v_mov_b32_dpp v142, v18 quad_perm:[1,0,3,2] row_mask:0xf bank_mask:0xf
	v_perm_b32 v143, v142, v18, v140
	ds_write_b32 v141, v143 offset:9216
	v_mov_b32_dpp v144, v19 quad_perm:[1,0,3,2] row_mask:0xf bank_mask:0xf
	v_perm_b32 v145, v144, v19, v140
	ds_write_b32 v141, v145 offset:9504
	v_mov_b32_dpp v146, v20 quad_perm:[1,0,3,2] row_mask:0xf bank_mask:0xf
	v_perm_b32 v147, v146, v20, v140
	ds_write_b32 v141, v147 offset:9792
	v_mov_b32_dpp v148, v21 quad_perm:[1,0,3,2] row_mask:0xf bank_mask:0xf
	v_perm_b32 v149, v148, v21, v140
	ds_write_b32 v141, v149 offset:10080
	s_waitcnt vmcnt(3)
	v_mov_b32_dpp v142, v12 quad_perm:[1,0,3,2] row_mask:0xf bank_mask:0xf
	v_perm_b32 v143, v142, v12, v140
	ds_write_b32 v141, v143 offset:18432
	v_mov_b32_dpp v144, v13 quad_perm:[1,0,3,2] row_mask:0xf bank_mask:0xf
	v_perm_b32 v145, v144, v13, v140
	ds_write_b32 v141, v145 offset:18720
	v_mov_b32_dpp v146, v14 quad_perm:[1,0,3,2] row_mask:0xf bank_mask:0xf
	v_perm_b32 v147, v146, v14, v140
	ds_write_b32 v141, v147 offset:19008
	v_mov_b32_dpp v148, v15 quad_perm:[1,0,3,2] row_mask:0xf bank_mask:0xf
	v_perm_b32 v149, v148, v15, v140
	ds_write_b32 v141, v149 offset:19296
	s_waitcnt vmcnt(2)
	v_mov_b32_dpp v142, v4 quad_perm:[1,0,3,2] row_mask:0xf bank_mask:0xf
	v_perm_b32 v143, v142, v4, v140
	ds_write_b32 v141, v143 offset:27648
	v_mov_b32_dpp v144, v5 quad_perm:[1,0,3,2] row_mask:0xf bank_mask:0xf
	v_perm_b32 v145, v144, v5, v140
	ds_write_b32 v141, v145 offset:27936
	v_mov_b32_dpp v146, v6 quad_perm:[1,0,3,2] row_mask:0xf bank_mask:0xf
	v_perm_b32 v147, v146, v6, v140
	ds_write_b32 v141, v147 offset:28224
	v_mov_b32_dpp v148, v7 quad_perm:[1,0,3,2] row_mask:0xf bank_mask:0xf
	v_perm_b32 v149, v148, v7, v140
	ds_write_b32 v141, v149 offset:28512
	s_waitcnt vmcnt(1)
	v_mov_b32_dpp v142, v8 quad_perm:[1,0,3,2] row_mask:0xf bank_mask:0xf
	v_perm_b32 v143, v142, v8, v140
	ds_write_b32 v141, v143 offset:36864
	v_mov_b32_dpp v144, v9 quad_perm:[1,0,3,2] row_mask:0xf bank_mask:0xf
	v_perm_b32 v145, v144, v9, v140
	ds_write_b32 v141, v145 offset:37152
	v_mov_b32_dpp v146, v10 quad_perm:[1,0,3,2] row_mask:0xf bank_mask:0xf
	v_perm_b32 v147, v146, v10, v140
	ds_write_b32 v141, v147 offset:37440
	v_mov_b32_dpp v148, v11 quad_perm:[1,0,3,2] row_mask:0xf bank_mask:0xf
	v_perm_b32 v149, v148, v11, v140
	ds_write_b32 v141, v149 offset:37728
	s_waitcnt vmcnt(0)
	v_mov_b32_dpp v142, v0 quad_perm:[1,0,3,2] row_mask:0xf bank_mask:0xf
	v_perm_b32 v143, v142, v0, v140
	ds_write_b32 v141, v143 offset:46080
	v_mov_b32_dpp v144, v1 quad_perm:[1,0,3,2] row_mask:0xf bank_mask:0xf
	v_perm_b32 v145, v144, v1, v140
	ds_write_b32 v141, v145 offset:46368
	v_mov_b32_dpp v146, v2 quad_perm:[1,0,3,2] row_mask:0xf bank_mask:0xf
	v_perm_b32 v147, v146, v2, v140
	ds_write_b32 v141, v147 offset:46656
	v_mov_b32_dpp v148, v3 quad_perm:[1,0,3,2] row_mask:0xf bank_mask:0xf
	v_perm_b32 v149, v148, v3, v140
	ds_write_b32 v141, v149 offset:46944
	s_waitcnt lgkmcnt(0)
	s_barrier
; __device__ __forceinline__ unsigned pk2(float lo, float hi) { return pg8::cvt_pk_bf16(lo, hi); }
; __device__ __forceinline__ f32x4 mma16(bf16x8 a, bf16x8 b, f32x4 c) { return __builtin_amdgcn_mfma_f32_16x16x32_bf16(a, b, c, 0, 0, 0); }
; __device__ __forceinline__ void ma_ret_item(const Params& p, ldsp lds, int item) {
;     ...
; #pragma unroll
;         for (int ks = 0; ks < 2; ++ks) { const bf16x8 bf = ldfrag(VTt, (16 * wave + l15) * 72 + 32 * ks + 8 * q4);
; #pragma unroll
;             for (int i = 0; i < 16; ++i) acc[i] = mma16(ldfrag(KTt, (16 * i + l15) * 72 + 32 * ks + 8 * q4), bf, acc[i]); }
;         __syncthreads(); }
;     bf16_t* HL = (bf16_t*)(p.ws + WS_HL) + (((size_t)bh * 8 + sc) * 512 + es * 128 + 16 * wave + l15) * 256;
; #pragma unroll
;     for (int i = 0; i < 16; ++i) { u32x2 w; w.x = pk2(acc[i][0], acc[i][1]); w.y = pk2(acc[i][2], acc[i][3]); *(u32x2*)(HL + 16 * i + 4 * q4) = w; }
	ds_read_b128 v[0:3], v132
	ds_read_b128 v[4:7], v130 offset:36864
	ds_read_b128 v[8:11], v131
	ds_read_b128 v[12:15], v130 offset:36928
	ds_read_b128 v[18:21], v129
	ds_read_b128 v[22:25], v128
	s_waitcnt lgkmcnt(4)
	v_mfma_f32_16x16x32_bf16 v[0:3], v[0:3], v[4:7], v[26:29]
	s_ashr_i32 s1, s0, 31
	v_readlane_b32 s10, v255, 9
	s_lshl_b64 s[0:1], s[0:1], 12
	s_waitcnt lgkmcnt(3)
	v_mfma_f32_16x16x32_bf16 v[8:11], v[8:11], v[4:7], v[34:37]
	ds_read_b128 v[26:29], v127
	v_readlane_b32 s11, v255, 10
	s_or_b64 s[0:1], s[0:1], s[10:11]
	s_waitcnt lgkmcnt(2)
	v_mfma_f32_16x16x32_bf16 v[18:21], v[18:21], v[4:7], v[38:41]
	ds_read_b128 v[34:37], v126
	s_ashr_i32 s9, s8, 31
	s_add_i32 s12, s12, 1
	s_waitcnt lgkmcnt(2)
	v_mfma_f32_16x16x32_bf16 v[22:25], v[22:25], v[4:7], v[42:45]
	ds_read_b128 v[38:41], v125
	s_cmp_eq_u32 s12, 4
	s_nop 0
	ds_read_b128 v[42:45], v124
	s_waitcnt lgkmcnt(3)
	v_mfma_f32_16x16x32_bf16 v[26:29], v[26:29], v[4:7], v[46:49]
	s_waitcnt lgkmcnt(2)
	v_mfma_f32_16x16x32_bf16 v[34:37], v[34:37], v[4:7], v[50:53]
	s_nop 0
	ds_read_b128 v[46:49], v123
	s_nop 0
	ds_read_b128 v[50:53], v122
	s_waitcnt lgkmcnt(3)
	v_mfma_f32_16x16x32_bf16 v[38:41], v[38:41], v[4:7], v[54:57]
	s_waitcnt lgkmcnt(2)
	v_mfma_f32_16x16x32_bf16 v[42:45], v[42:45], v[4:7], v[58:61]
	s_nop 0
	ds_read_b128 v[54:57], v121
	s_nop 0
	ds_read_b128 v[58:61], v120
	s_waitcnt lgkmcnt(3)
	v_mfma_f32_16x16x32_bf16 v[46:49], v[46:49], v[4:7], v[62:65]
	s_waitcnt lgkmcnt(2)
	v_mfma_f32_16x16x32_bf16 v[50:53], v[50:53], v[4:7], v[66:69]
	s_nop 0
	ds_read_b128 v[62:65], v119
	s_nop 0
	ds_read_b128 v[66:69], v118
	s_waitcnt lgkmcnt(3)
	v_mfma_f32_16x16x32_bf16 v[54:57], v[54:57], v[4:7], v[70:73]
	s_waitcnt lgkmcnt(2)
	v_mfma_f32_16x16x32_bf16 v[58:61], v[58:61], v[4:7], v[74:77]
	s_nop 0
	ds_read_b128 v[70:73], v117
	s_nop 0
	ds_read_b128 v[74:77], v116
	s_waitcnt lgkmcnt(3)
	v_mfma_f32_16x16x32_bf16 v[62:65], v[62:65], v[4:7], v[78:81]
	s_waitcnt lgkmcnt(2)
	v_mfma_f32_16x16x32_bf16 v[66:69], v[66:69], v[4:7], v[82:85]
	s_nop 0
	ds_read_b128 v[78:81], v115
	s_waitcnt lgkmcnt(2)
	v_mfma_f32_16x16x32_bf16 v[70:73], v[70:73], v[4:7], v[86:89]
	s_waitcnt lgkmcnt(1)
	v_mfma_f32_16x16x32_bf16 v[4:7], v[74:77], v[4:7], v[30:33]
	ds_read_b128 v[74:77], v113
	s_nop 1
	ds_read_b128 v[30:33], v114
	s_waitcnt lgkmcnt(0)
	v_mfma_f32_16x16x32_bf16 v[8:11], v[30:33], v[12:15], v[8:11]
	ds_read_b128 v[30:33], v112
	v_mfma_f32_16x16x32_bf16 v[18:21], v[74:77], v[12:15], v[18:21]
	ds_read_b128 v[74:77], v111
	s_waitcnt lgkmcnt(1)
	v_mfma_f32_16x16x32_bf16 v[22:25], v[30:33], v[12:15], v[22:25]
	ds_read_b128 v[30:33], v110
	s_waitcnt lgkmcnt(1)
	v_mfma_f32_16x16x32_bf16 v[26:29], v[74:77], v[12:15], v[26:29]
	ds_read_b128 v[74:77], v109
	s_waitcnt lgkmcnt(1)
	v_mfma_f32_16x16x32_bf16 v[30:33], v[30:33], v[12:15], v[34:37]
	s_nop 2
	ds_read_b128 v[34:37], v108
	s_waitcnt lgkmcnt(1)
	v_mfma_f32_16x16x32_bf16 v[38:41], v[74:77], v[12:15], v[38:41]
	ds_read_b128 v[74:77], v107
	s_waitcnt lgkmcnt(1)
	v_mfma_f32_16x16x32_bf16 v[34:37], v[34:37], v[12:15], v[42:45]
	s_nop 2
	ds_read_b128 v[42:45], v106
	s_waitcnt lgkmcnt(1)
	v_mfma_f32_16x16x32_bf16 v[46:49], v[74:77], v[12:15], v[46:49]
	ds_read_b128 v[74:77], v105
	s_waitcnt lgkmcnt(1)
	v_mfma_f32_16x16x32_bf16 v[42:45], v[42:45], v[12:15], v[50:53]
	s_nop 2
	ds_read_b128 v[50:53], v104
	v_mfma_f32_16x16x32_bf16 v[0:3], v[78:81], v[12:15], v[0:3]
	s_waitcnt lgkmcnt(1)
	v_mfma_f32_16x16x32_bf16 v[54:57], v[74:77], v[12:15], v[54:57]
	ds_read_b128 v[74:77], v103
	ds_read_b128 v[78:81], v102
	s_waitcnt lgkmcnt(2)
	v_mfma_f32_16x16x32_bf16 v[50:53], v[50:53], v[12:15], v[58:61]
	s_nop 2
	ds_read_b128 v[58:61], v101
	ds_read_b128 v[82:85], v16
	s_waitcnt lgkmcnt(0)
	s_barrier
	v_mfma_f32_16x16x32_bf16 v[58:61], v[58:61], v[12:15], v[70:73]
	v_cvt_pk_bf16_f32 v0, v0, v1
	v_cvt_pk_bf16_f32 v1, v2, v3
	v_mfma_f32_16x16x32_bf16 v[62:65], v[74:77], v[12:15], v[62:65]
	s_nop 1
	v_or_b32_e32 v70, s0, v95
	v_mov_b32_e32 v71, s1
	v_lshl_add_u64 v[70:71], v[70:71], 0, s[8:9]
	v_readlane_b32 s0, v253, 34
	v_mfma_f32_16x16x32_bf16 v[66:69], v[78:81], v[12:15], v[66:69]
	v_readlane_b32 s1, v253, 35
	v_mov_b32_e32 v95, v17
	v_mfma_f32_16x16x32_bf16 v[4:7], v[82:85], v[12:15], v[4:7]
	v_lshlrev_b64 v[12:13], 9, v[70:71]
	v_lshl_add_u64 v[12:13], s[0:1], 0, v[12:13]
	v_lshl_add_u64 v[12:13], v[12:13], 0, v[94:95]
	global_store_dwordx2 v[12:13], v[0:1], off
	v_cvt_pk_bf16_f32 v0, v8, v9
	v_cvt_pk_bf16_f32 v1, v10, v11
	global_store_dwordx2 v[12:13], v[0:1], off offset:32
	v_cvt_pk_bf16_f32 v0, v18, v19
	v_cvt_pk_bf16_f32 v1, v20, v21
	global_store_dwordx2 v[12:13], v[0:1], off offset:64
	v_cvt_pk_bf16_f32 v0, v22, v23
	v_cvt_pk_bf16_f32 v1, v24, v25
	global_store_dwordx2 v[12:13], v[0:1], off offset:96
	v_cvt_pk_bf16_f32 v0, v26, v27
	v_cvt_pk_bf16_f32 v1, v28, v29
	global_store_dwordx2 v[12:13], v[0:1], off offset:128
	v_cvt_pk_bf16_f32 v0, v30, v31
	v_cvt_pk_bf16_f32 v1, v32, v33
	global_store_dwordx2 v[12:13], v[0:1], off offset:160
	v_cvt_pk_bf16_f32 v0, v38, v39
	v_cvt_pk_bf16_f32 v1, v40, v41
	global_store_dwordx2 v[12:13], v[0:1], off offset:192
	v_cvt_pk_bf16_f32 v0, v34, v35
	v_cvt_pk_bf16_f32 v1, v36, v37
	global_store_dwordx2 v[12:13], v[0:1], off offset:224
	v_cvt_pk_bf16_f32 v0, v46, v47
	v_cvt_pk_bf16_f32 v1, v48, v49
	global_store_dwordx2 v[12:13], v[0:1], off offset:256
	v_cvt_pk_bf16_f32 v0, v42, v43
	v_cvt_pk_bf16_f32 v1, v44, v45
	global_store_dwordx2 v[12:13], v[0:1], off offset:288
	v_cvt_pk_bf16_f32 v0, v54, v55
	v_cvt_pk_bf16_f32 v1, v56, v57
	global_store_dwordx2 v[12:13], v[0:1], off offset:320
	v_cvt_pk_bf16_f32 v0, v50, v51
	v_cvt_pk_bf16_f32 v1, v52, v53
	global_store_dwordx2 v[12:13], v[0:1], off offset:352
	v_cvt_pk_bf16_f32 v0, v62, v63
	v_cvt_pk_bf16_f32 v1, v64, v65
	global_store_dwordx2 v[12:13], v[0:1], off offset:384
	v_cvt_pk_bf16_f32 v0, v66, v67
	v_cvt_pk_bf16_f32 v1, v68, v69
	global_store_dwordx2 v[12:13], v[0:1], off offset:416
	v_cvt_pk_bf16_f32 v0, v58, v59
	v_cvt_pk_bf16_f32 v1, v60, v61
	global_store_dwordx2 v[12:13], v[0:1], off offset:448
	v_cvt_pk_bf16_f32 v0, v4, v5
	v_cvt_pk_bf16_f32 v1, v6, v7
	global_store_dwordx2 v[12:13], v[0:1], off offset:480
	s_cbranch_scc0 .LBB0_677

; #define LAS __attribute__((address_space(3)))
; template <int F> __device__ __forceinline__ void st_rows(ldsp dst, int dp, const u32x4 (&r)[(64 * (F / 8)) / NTHREADS], int tid) {
;     constexpr int G8 = F / 8;
; #pragma unroll
;     for (int it = 0; it < (64 * G8) / NTHREADS; ++it) { const int idx = tid + it * NTHREADS; const int s = idx / G8, g = idx % G8; *(LAS u32x4*)(dst + (size_t)(s * dp + g * 8) * 2) = r[it]; }
; }
; template <int F> __device__ __forceinline__ void ld_T(u32x4 (&r)[F / 64], const bf16_t* src, size_t sp, int wave, int lane) {
;     const bf16_t* base = src + (size_t)(32 * (wave & 1) + (lane & 31)) * sp + (2 * (wave >> 1) + (lane >> 5)) * 8;
; #pragma unroll
;     for (int it = 0; it < F / 64; ++it) r[it] = *(const u32x4*)(base + 64 * it);
; }
; template <int F> __device__ __forceinline__ void st_T(ldsp dst, int dp_unused, const u32x4 (&r)[F / 64], int wave, int lane) {
;     ldsp base = dst + (size_t)((2 * (wave >> 1) + (lane >> 5)) * 8 * 72 + 32 * (wave & 1) + (lane & 31)) * 2;
; #pragma unroll
;     for (int it = 0; it < F / 64; ++it) { const u32x4 w = r[it];
; #pragma unroll
;         for (int i = 0; i < 4; ++i) {
;             *(LAS bf16_t*)(base + (64 * it + 2 * i) * 144) = (bf16_t)(w[i] & 0xffffu);
;             *(LAS bf16_t*)(base + (64 * it + 2 * i + 1) * 144) = (bf16_t)(w[i] >> 16); } }
; }
; template <int TY> __device__ __forceinline__ void mc_item(const Params& p, ldsp lds, int item) {
;     ...
;     for (int j = 0; j <= jc; ++j) { const size_t rowj = (size_t)b * 2048 + (sc * NB + j) * 64;
;         if constexpr (TY == 2) { st_rows<256>(KTs, PQ, kr, tid); st_T<512>(VTs, 72, vr, wave, lane); }
.LBB0_880:
	v_add_u32_e32 v16, v206, v203
	s_waitcnt vmcnt(11)
	ds_write_b128 v16, v[130:133] offset:33792
	v_add_u32_e32 v16, v207, v204
	s_waitcnt vmcnt(10)
	ds_write_b128 v16, v[126:129] offset:33792
	v_add_u32_e32 v16, v208, v205
	s_waitcnt vmcnt(9)
	ds_write_b128 v16, v[122:125] offset:33792
	v_add_u32_e32 v16, v210, v209
	s_waitcnt vmcnt(8)
	ds_write_b128 v16, v[118:121] offset:33792
	s_waitcnt vmcnt(7)
	v_and_b32_e32 v134, 1, v161
	v_sub_u32_e32 v135, 0, v134
	v_mov_b32_e32 v136, 0x5040100
	v_mov_b32_e32 v137, 0x3020706
	v_bfi_b32 v166, v135, v137, v136
	v_mul_u32_u24_e32 v167, 0x8e, v134
	v_add_u32_e32 v167, v167, v162
	v_mov_b32_dpp v168, v26 quad_perm:[1,0,3,2] row_mask:0xf bank_mask:0xf
	v_perm_b32 v169, v168, v26, v166
	ds_write_b32 v167, v169
	v_mov_b32_dpp v172, v27 quad_perm:[1,0,3,2] row_mask:0xf bank_mask:0xf
	v_perm_b32 v173, v172, v27, v166
	ds_write_b32 v167, v173 offset:288
	v_mov_b32_dpp v174, v28 quad_perm:[1,0,3,2] row_mask:0xf bank_mask:0xf
	v_perm_b32 v175, v174, v28, v166
	ds_write_b32 v167, v175 offset:576
	v_mov_b32_dpp v176, v29 quad_perm:[1,0,3,2] row_mask:0xf bank_mask:0xf
	v_perm_b32 v177, v176, v29, v166
	ds_write_b32 v167, v177 offset:864
	s_waitcnt vmcnt(6)
	v_mov_b32_dpp v168, v22 quad_perm:[1,0,3,2] row_mask:0xf bank_mask:0xf
	v_perm_b32 v169, v168, v22, v166
	ds_write_b32 v167, v169 offset:9216
	v_mov_b32_dpp v172, v23 quad_perm:[1,0,3,2] row_mask:0xf bank_mask:0xf
	v_perm_b32 v173, v172, v23, v166
	ds_write_b32 v167, v173 offset:9504
	v_mov_b32_dpp v174, v24 quad_perm:[1,0,3,2] row_mask:0xf bank_mask:0xf
	v_perm_b32 v175, v174, v24, v166
	ds_write_b32 v167, v175 offset:9792
	v_mov_b32_dpp v176, v25 quad_perm:[1,0,3,2] row_mask:0xf bank_mask:0xf
	v_perm_b32 v177, v176, v25, v166
	ds_write_b32 v167, v177 offset:10080
	s_waitcnt vmcnt(5)
	v_mov_b32_dpp v168, v18 quad_perm:[1,0,3,2] row_mask:0xf bank_mask:0xf
	v_perm_b32 v169, v168, v18, v166
	ds_write_b32 v167, v169 offset:18432
	v_mov_b32_dpp v172, v19 quad_perm:[1,0,3,2] row_mask:0xf bank_mask:0xf
	v_perm_b32 v173, v172, v19, v166
	ds_write_b32 v167, v173 offset:18720
	v_mov_b32_dpp v174, v20 quad_perm:[1,0,3,2] row_mask:0xf bank_mask:0xf
	v_perm_b32 v175, v174, v20, v166
	ds_write_b32 v167, v175 offset:19008
	v_mov_b32_dpp v176, v21 quad_perm:[1,0,3,2] row_mask:0xf bank_mask:0xf
	v_perm_b32 v177, v176, v21, v166
	ds_write_b32 v167, v177 offset:19296
	s_waitcnt vmcnt(4)
	v_mov_b32_dpp v168, v12 quad_perm:[1,0,3,2] row_mask:0xf bank_mask:0xf
	v_perm_b32 v169, v168, v12, v166
	ds_write_b32 v167, v169 offset:27648
	v_mov_b32_dpp v172, v13 quad_perm:[1,0,3,2] row_mask:0xf bank_mask:0xf
	v_perm_b32 v173, v172, v13, v166
	ds_write_b32 v167, v173 offset:27936
	v_mov_b32_dpp v174, v14 quad_perm:[1,0,3,2] row_mask:0xf bank_mask:0xf
	v_perm_b32 v175, v174, v14, v166
	ds_write_b32 v167, v175 offset:28224
	v_mov_b32_dpp v176, v15 quad_perm:[1,0,3,2] row_mask:0xf bank_mask:0xf
	v_perm_b32 v177, v176, v15, v166
	ds_write_b32 v167, v177 offset:28512
	s_waitcnt vmcnt(3)
	v_mov_b32_dpp v168, v8 quad_perm:[1,0,3,2] row_mask:0xf bank_mask:0xf
	v_perm_b32 v169, v168, v8, v166
	ds_write_b32 v167, v169 offset:36864
	v_mov_b32_dpp v172, v9 quad_perm:[1,0,3,2] row_mask:0xf bank_mask:0xf
	v_perm_b32 v173, v172, v9, v166
	ds_write_b32 v167, v173 offset:37152
	v_mov_b32_dpp v174, v10 quad_perm:[1,0,3,2] row_mask:0xf bank_mask:0xf
	v_perm_b32 v175, v174, v10, v166
	ds_write_b32 v167, v175 offset:37440
	v_mov_b32_dpp v176, v11 quad_perm:[1,0,3,2] row_mask:0xf bank_mask:0xf
	v_perm_b32 v177, v176, v11, v166
	ds_write_b32 v167, v177 offset:37728
	s_waitcnt vmcnt(2)
	v_mov_b32_dpp v168, v4 quad_perm:[1,0,3,2] row_mask:0xf bank_mask:0xf
	v_perm_b32 v169, v168, v4, v166
	ds_write_b32 v167, v169 offset:46080
	v_mov_b32_dpp v172, v5 quad_perm:[1,0,3,2] row_mask:0xf bank_mask:0xf
	v_perm_b32 v173, v172, v5, v166
	ds_write_b32 v167, v173 offset:46368
	v_mov_b32_dpp v174, v6 quad_perm:[1,0,3,2] row_mask:0xf bank_mask:0xf
	v_perm_b32 v175, v174, v6, v166
	ds_write_b32 v167, v175 offset:46656
	v_mov_b32_dpp v176, v7 quad_perm:[1,0,3,2] row_mask:0xf bank_mask:0xf
	v_perm_b32 v177, v176, v7, v166
	ds_write_b32 v167, v177 offset:46944
	s_waitcnt vmcnt(1)
	v_mov_b32_dpp v168, v0 quad_perm:[1,0,3,2] row_mask:0xf bank_mask:0xf
	v_perm_b32 v169, v168, v0, v166
	ds_write_b32 v167, v169 offset:55296
	v_mov_b32_dpp v172, v1 quad_perm:[1,0,3,2] row_mask:0xf bank_mask:0xf
	v_perm_b32 v173, v172, v1, v166
	ds_write_b32 v167, v173 offset:55584
	v_mov_b32_dpp v174, v2 quad_perm:[1,0,3,2] row_mask:0xf bank_mask:0xf
	v_perm_b32 v175, v174, v2, v166
	ds_write_b32 v167, v175 offset:55872
	v_mov_b32_dpp v176, v3 quad_perm:[1,0,3,2] row_mask:0xf bank_mask:0xf
	v_perm_b32 v177, v176, v3, v166
	ds_write_b32 v167, v177 offset:56160
	s_waitcnt vmcnt(0)
	v_mov_b32_dpp v168, v98 quad_perm:[1,0,3,2] row_mask:0xf bank_mask:0xf
	v_perm_b32 v169, v168, v98, v166
	ds_write_b32 v167, v169 offset:64512
	v_mov_b32_dpp v172, v99 quad_perm:[1,0,3,2] row_mask:0xf bank_mask:0xf
	v_perm_b32 v173, v172, v99, v166
	ds_write_b32 v167, v173 offset:64800
	v_mov_b32_dpp v174, v100 quad_perm:[1,0,3,2] row_mask:0xf bank_mask:0xf
	v_perm_b32 v175, v174, v100, v166
	ds_write_b32 v167, v175 offset:65088
	v_mov_b32_dpp v176, v101 quad_perm:[1,0,3,2] row_mask:0xf bank_mask:0xf
	v_perm_b32 v177, v176, v101, v166
	ds_write_b32 v167, v177 offset:65376
	v_lshl_add_u64 v[0:1], v[140:141], 0, s[38:39]
	s_waitcnt lgkmcnt(0)
	s_barrier
; #define LAS __attribute__((address_space(3)))
; __device__ __forceinline__ unsigned pk2(float lo, float hi) { return pg8::cvt_pk_bf16(lo, hi); }
; __device__ __forceinline__ f32x4 mma16(bf16x8 a, bf16x8 b, f32x4 c) { return __builtin_amdgcn_mfma_f32_16x16x32_bf16(a, b, c, 0, 0, 0); }
; #define BSYNC() do { asm volatile("s_waitcnt vmcnt(0) lgkmcnt(0)" ::: "memory"); __syncthreads(); } while (0)
; template <int TY> __device__ __forceinline__ void mc_item(const Params& p, ldsp lds, int item) {
;     ...
;         if constexpr (TY == 2) { __syncthreads(); if (j < jc) { const size_t rown = rowj + 64; ld_rows<256>(kr, Pb + rown * NO + O_K + h * 256, NO, tid); ld_T<512>(vr, Pb + rown * NO + voff, NO, wave, lane); } }
;         else BSYNC();
;         { f32x4 c0 = (f32x4){0.f, 0.f, 0.f, 0.f}, c1 = c0;
; #pragma unroll
;           for (int ks = 0; ks < DK / 32; ++ks) { const bf16x8 bq = ldfrag(QX, (16 * tt + l15) * PQ + 32 * ks + 8 * q4);
;               c0 = mma16(ldfrag(KTs, (16 * (2 * sp) + l15) * PQ + 32 * ks + 8 * q4), bq, c0);
;               c1 = mma16(ldfrag(KTs, (16 * (2 * sp + 1) + l15) * PQ + 32 * ks + 8 * q4), bq, c1); }
;           const int t = 16 * tt + l15;
;           const int tl = (j == jc) ? t : 4096;
; #pragma unroll
;           for (int jj = 0; jj < 4; ++jj) { if (32 * sp + 4 * q4 + jj > tl) c0[jj] = 0.f; if (32 * sp + 16 + 4 * q4 + jj > tl) c1[jj] = 0.f; }
;           u32x2 w; w.x = pk2(c0[0], c0[1]); w.y = pk2(c0[2], c0[3]); *(LAS u32x2*)(Pm + (size_t)(t * 72 + 32 * sp + 4 * q4) * 2) = w;
;           w.x = pk2(c1[0], c1[1]); w.y = pk2(c1[2], c1[3]); *(LAS u32x2*)(Pm + (size_t)(t * 72 + 32 * sp + 16 + 4 * q4) * 2) = w; }
	global_load_dwordx4 v[130:133], v[0:1], off
	v_lshl_add_u64 v[0:1], v[142:143], 0, s[38:39]
	global_load_dwordx4 v[126:129], v[0:1], off
	v_lshl_add_u64 v[0:1], v[144:145], 0, s[38:39]
	global_load_dwordx4 v[122:125], v[0:1], off
	v_lshl_add_u64 v[0:1], v[146:147], 0, s[38:39]
	v_lshl_add_u64 v[98:99], v[148:149], 0, s[38:39]
	v_add_u32_e32 v16, 0, v163
	v_add_u32_e32 v166, 0, v217
	v_add_u32_e32 v167, 0, v216
	global_load_dwordx4 v[118:121], v[0:1], off
	global_load_dwordx4 v[26:29], v[98:99], off offset:-512
	global_load_dwordx4 v[22:25], v[98:99], off offset:-384
	global_load_dwordx4 v[18:21], v[98:99], off offset:-256
	global_load_dwordx4 v[12:15], v[98:99], off offset:-128
	global_load_dwordx4 v[8:11], v[98:99], off
	global_load_dwordx4 v[4:7], v[98:99], off offset:128
	global_load_dwordx4 v[0:3], v[98:99], off offset:256
	s_nop 0
	global_load_dwordx4 v[98:101], v[98:99], off offset:384
	ds_read_b128 v[134:137], v16
	ds_read_b128 v[172:175], v166 offset:33792
	ds_read_b128 v[176:179], v167 offset:33792
	s_waitcnt lgkmcnt(1)
	v_mfma_f32_16x16x32_bf16 v[172:175], v[172:175], v[134:137], 0
	s_add_u32 s38, s38, 0xc0000
	s_addc_u32 s39, s39, 0
	s_cmp_eq_u32 s9, s38
	s_waitcnt lgkmcnt(0)
	v_mfma_f32_16x16x32_bf16 v[134:137], v[176:179], v[134:137], 0
	ds_read_b128 v[176:179], v16 offset:64
	ds_read_b128 v[180:183], v166 offset:33856
	s_waitcnt lgkmcnt(0)
	v_mfma_f32_16x16x32_bf16 v[172:175], v[180:183], v[176:179], v[172:175]
	ds_read_b128 v[180:183], v167 offset:33856
	s_waitcnt lgkmcnt(0)
	v_mfma_f32_16x16x32_bf16 v[134:137], v[180:183], v[176:179], v[134:137]
	ds_read_b128 v[176:179], v16 offset:128
	ds_read_b128 v[180:183], v166 offset:33920
	s_waitcnt lgkmcnt(0)
	v_mfma_f32_16x16x32_bf16 v[172:175], v[180:183], v[176:179], v[172:175]
	ds_read_b128 v[180:183], v167 offset:33920
	s_waitcnt lgkmcnt(0)
	v_mfma_f32_16x16x32_bf16 v[134:137], v[180:183], v[176:179], v[134:137]
	ds_read_b128 v[176:179], v16 offset:192
	ds_read_b128 v[180:183], v166 offset:33984
	s_waitcnt lgkmcnt(0)
	v_mfma_f32_16x16x32_bf16 v[172:175], v[180:183], v[176:179], v[172:175]
	ds_read_b128 v[180:183], v167 offset:33984
	s_waitcnt lgkmcnt(0)
	v_mfma_f32_16x16x32_bf16 v[134:137], v[180:183], v[176:179], v[134:137]
	ds_read_b128 v[176:179], v16 offset:256
	ds_read_b128 v[180:183], v166 offset:34048
	s_waitcnt lgkmcnt(0)
	v_mfma_f32_16x16x32_bf16 v[172:175], v[180:183], v[176:179], v[172:175]
	ds_read_b128 v[180:183], v167 offset:34048
	s_waitcnt lgkmcnt(0)
	v_mfma_f32_16x16x32_bf16 v[134:137], v[180:183], v[176:179], v[134:137]
	ds_read_b128 v[176:179], v16 offset:320
	ds_read_b128 v[180:183], v166 offset:34112
	s_waitcnt lgkmcnt(0)
	v_mfma_f32_16x16x32_bf16 v[172:175], v[180:183], v[176:179], v[172:175]
	ds_read_b128 v[180:183], v167 offset:34112
	s_waitcnt lgkmcnt(0)
	v_mfma_f32_16x16x32_bf16 v[134:137], v[180:183], v[176:179], v[134:137]
	ds_read_b128 v[176:179], v16 offset:384
	ds_read_b128 v[180:183], v166 offset:34176
	s_waitcnt lgkmcnt(0)
	v_mfma_f32_16x16x32_bf16 v[172:175], v[180:183], v[176:179], v[172:175]
	ds_read_b128 v[180:183], v167 offset:34176
	s_waitcnt lgkmcnt(0)
	v_mfma_f32_16x16x32_bf16 v[134:137], v[180:183], v[176:179], v[134:137]
	ds_read_b128 v[176:179], v16 offset:448
	ds_read_b128 v[180:183], v166 offset:34240
	v_mov_b32_e32 v16, s41
	s_waitcnt lgkmcnt(0)
	v_mfma_f32_16x16x32_bf16 v[172:175], v[180:183], v[176:179], v[172:175]
	ds_read_b128 v[180:183], v167 offset:34240
	s_waitcnt lgkmcnt(0)
	v_mfma_f32_16x16x32_bf16 v[134:137], v[180:183], v[176:179], v[134:137]
	v_mov_b32_e32 v176, s41
	s_nop 3
	v_cndmask_b32_e64 v16, v172, v16, s[20:21]
	v_cndmask_b32_e64 v168, v175, 0, s[16:17]
	s_nop 0
	v_cndmask_b32_e32 v166, v134, v176, vcc
	v_cndmask_b32_e64 v134, v173, 0, s[10:11]
	v_cndmask_b32_e64 v167, v135, 0, s[12:13]
	v_cndmask_b32_e64 v135, v174, 0, s[10:11]
	v_cvt_pk_bf16_f32 v134, v16, v134
	v_add_u32_e32 v16, 0, v156
	v_cvt_pk_bf16_f32 v135, v135, v168
	v_add_u32_e32 v16, 0x22800, v16
	v_cndmask_b32_e64 v136, v136, 0, s[14:15]
	v_cndmask_b32_e64 v137, v137, 0, s[18:19]
	ds_write_b64 v16, v[134:135]
	v_cvt_pk_bf16_f32 v134, v166, v167
	v_cvt_pk_bf16_f32 v135, v136, v137
	ds_write_b64 v16, v[134:135] offset:32
	v_add_u32_e32 v16, v154, v201
	v_add_u32_e32 v166, v139, v202
	s_waitcnt lgkmcnt(0)
	s_barrier
; __device__ __forceinline__ f32x4 mma16(bf16x8 a, bf16x8 b, f32x4 c) { return __builtin_amdgcn_mfma_f32_16x16x32_bf16(a, b, c, 0, 0, 0); }
; #define BSYNC() do { asm volatile("s_waitcnt vmcnt(0) lgkmcnt(0)" ::: "memory"); __syncthreads(); } while (0)
; template <int TY> __device__ __forceinline__ void mc_item(const Params& p, ldsp lds, int item) {
;     ...
;         if constexpr (TY == 2) __syncthreads(); else BSYNC();
; #pragma unroll
;         for (int ks = 0; ks < 2; ++ks) { bf16x8 pb[4];
; #pragma unroll
;             for (int tk = 0; tk < 4; ++tk) pb[tk] = ldfrag(Pm, (16 * tk + l15) * 72 + 32 * ks + 8 * q4);
; #pragma unroll
;             for (int ei = 0; ei < ET; ++ei) { const bf16x8 va = ldfrag(VTs, (16 * (wave * ET + ei) + l15) * 72 + 32 * ks + 8 * q4);
; #pragma unroll
;                 for (int tk = 0; tk < 4; ++tk) acc[ei][tk] = mma16(va, pb[tk], acc[ei][tk]); } }
;         if constexpr (TY == 2) __syncthreads(); else BSYNC(); }
	ds_read_b128 v[134:137], v16
	ds_read_b128 v[172:175], v16 offset:2304
	ds_read_b128 v[176:179], v16 offset:4608
	ds_read_b128 v[180:183], v16 offset:6912
	ds_read_b128 v[186:189], v166
	s_waitcnt lgkmcnt(0)
	v_mfma_f32_16x16x32_bf16 v[62:65], v[186:189], v[134:137], v[62:65]
	v_mfma_f32_16x16x32_bf16 v[58:61], v[186:189], v[172:175], v[58:61]
	v_mfma_f32_16x16x32_bf16 v[50:53], v[186:189], v[176:179], v[50:53]
	v_mfma_f32_16x16x32_bf16 v[42:45], v[186:189], v[180:183], v[42:45]
	ds_read_b128 v[186:189], v166 offset:2304
	s_waitcnt lgkmcnt(0)
	v_mfma_f32_16x16x32_bf16 v[66:69], v[186:189], v[134:137], v[66:69]
	v_mfma_f32_16x16x32_bf16 v[70:73], v[186:189], v[172:175], v[70:73]
	v_mfma_f32_16x16x32_bf16 v[74:77], v[186:189], v[176:179], v[74:77]
	v_mfma_f32_16x16x32_bf16 v[78:81], v[186:189], v[180:183], v[78:81]
	ds_read_b128 v[186:189], v166 offset:4608
	s_waitcnt lgkmcnt(0)
	v_mfma_f32_16x16x32_bf16 v[82:85], v[186:189], v[134:137], v[82:85]
	v_mfma_f32_16x16x32_bf16 v[86:89], v[186:189], v[172:175], v[86:89]
	v_mfma_f32_16x16x32_bf16 v[90:93], v[186:189], v[176:179], v[90:93]
	v_mfma_f32_16x16x32_bf16 v[94:97], v[186:189], v[180:183], v[94:97]
	ds_read_b128 v[186:189], v166 offset:6912
	s_waitcnt lgkmcnt(0)
	v_mfma_f32_16x16x32_bf16 v[102:105], v[186:189], v[134:137], v[102:105]
	v_mfma_f32_16x16x32_bf16 v[106:109], v[186:189], v[172:175], v[106:109]
	v_mfma_f32_16x16x32_bf16 v[110:113], v[186:189], v[176:179], v[110:113]
	v_mfma_f32_16x16x32_bf16 v[114:117], v[186:189], v[180:183], v[114:117]
	ds_read_b128 v[134:137], v16 offset:64
	ds_read_b128 v[172:175], v16 offset:2368
	ds_read_b128 v[176:179], v16 offset:4672
	ds_read_b128 v[180:183], v16 offset:6976
	ds_read_b128 v[186:189], v166 offset:64
	s_waitcnt lgkmcnt(0)
	v_mfma_f32_16x16x32_bf16 v[62:65], v[186:189], v[134:137], v[62:65]
	v_mfma_f32_16x16x32_bf16 v[58:61], v[186:189], v[172:175], v[58:61]
	v_mfma_f32_16x16x32_bf16 v[50:53], v[186:189], v[176:179], v[50:53]
	v_mfma_f32_16x16x32_bf16 v[42:45], v[186:189], v[180:183], v[42:45]
	ds_read_b128 v[186:189], v166 offset:2368
	s_waitcnt lgkmcnt(0)
	v_mfma_f32_16x16x32_bf16 v[66:69], v[186:189], v[134:137], v[66:69]
	v_mfma_f32_16x16x32_bf16 v[70:73], v[186:189], v[172:175], v[70:73]
	v_mfma_f32_16x16x32_bf16 v[74:77], v[186:189], v[176:179], v[74:77]
	v_mfma_f32_16x16x32_bf16 v[78:81], v[186:189], v[180:183], v[78:81]
	ds_read_b128 v[186:189], v166 offset:4672
	s_waitcnt lgkmcnt(0)
	v_mfma_f32_16x16x32_bf16 v[82:85], v[186:189], v[134:137], v[82:85]
	v_mfma_f32_16x16x32_bf16 v[86:89], v[186:189], v[172:175], v[86:89]
	v_mfma_f32_16x16x32_bf16 v[90:93], v[186:189], v[176:179], v[90:93]
	v_mfma_f32_16x16x32_bf16 v[94:97], v[186:189], v[180:183], v[94:97]
	ds_read_b128 v[186:189], v166 offset:6976
	s_waitcnt lgkmcnt(0)
	s_barrier
	v_mfma_f32_16x16x32_bf16 v[102:105], v[186:189], v[134:137], v[102:105]
	v_mfma_f32_16x16x32_bf16 v[106:109], v[186:189], v[172:175], v[106:109]
	v_mfma_f32_16x16x32_bf16 v[110:113], v[186:189], v[176:179], v[110:113]
	v_mfma_f32_16x16x32_bf16 v[114:117], v[186:189], v[180:183], v[114:117]
	s_cbranch_scc0 .LBB0_880
	s_movk_i32 s9, 0x90
	s_branch .LBB0_883

; #define LAS __attribute__((address_space(3)))
; template <int F> __device__ __forceinline__ void st_rows(ldsp dst, int dp, const u32x4 (&r)[(64 * (F / 8)) / NTHREADS], int tid) {
;     constexpr int G8 = F / 8;
; #pragma unroll
;     for (int it = 0; it < (64 * G8) / NTHREADS; ++it) { const int idx = tid + it * NTHREADS; const int s = idx / G8, g = idx % G8; *(LAS u32x4*)(dst + (size_t)(s * dp + g * 8) * 2) = r[it]; }
; }
; template <int F> __device__ __forceinline__ void ld_T(u32x4 (&r)[F / 64], const bf16_t* src, size_t sp, int wave, int lane) {
;     const bf16_t* base = src + (size_t)(32 * (wave & 1) + (lane & 31)) * sp + (2 * (wave >> 1) + (lane >> 5)) * 8;
; #pragma unroll
;     for (int it = 0; it < F / 64; ++it) r[it] = *(const u32x4*)(base + 64 * it);
; }
; template <int F> __device__ __forceinline__ void st_T(ldsp dst, int dp_unused, const u32x4 (&r)[F / 64], int wave, int lane) {
;     ldsp base = dst + (size_t)((2 * (wave >> 1) + (lane >> 5)) * 8 * 72 + 32 * (wave & 1) + (lane & 31)) * 2;
; #pragma unroll
;     for (int it = 0; it < F / 64; ++it) { const u32x4 w = r[it];
; #pragma unroll
;         for (int i = 0; i < 4; ++i) {
;             *(LAS bf16_t*)(base + (64 * it + 2 * i) * 144) = (bf16_t)(w[i] & 0xffffu);
;             *(LAS bf16_t*)(base + (64 * it + 2 * i + 1) * 144) = (bf16_t)(w[i] >> 16); } }
; }
; template <int TY> __device__ __forceinline__ void mc_item(const Params& p, ldsp lds, int item) {
;     ...
;     for (int j = 0; j <= jc; ++j) { const size_t rowj = (size_t)b * 2048 + (sc * NB + j) * 64;
;         if constexpr (TY == 2) { st_rows<256>(KTs, PQ, kr, tid); st_T<512>(VTs, 72, vr, wave, lane); }
.LBB0_883:
	v_add_u32_e32 v16, v206, v203
	s_waitcnt vmcnt(11)
	ds_write_b128 v16, v[130:133] offset:33792
	v_add_u32_e32 v16, v207, v204
	s_waitcnt vmcnt(10)
	ds_write_b128 v16, v[126:129] offset:33792
	v_add_u32_e32 v16, v208, v205
	s_waitcnt vmcnt(9)
	ds_write_b128 v16, v[122:125] offset:33792
	v_add_u32_e32 v16, v210, v209
	s_waitcnt vmcnt(8)
	ds_write_b128 v16, v[118:121] offset:33792
	s_waitcnt vmcnt(7)
	v_and_b32_e32 v134, 1, v161
	v_sub_u32_e32 v135, 0, v134
	v_mov_b32_e32 v136, 0x5040100
	v_mov_b32_e32 v137, 0x3020706
	v_bfi_b32 v140, v135, v137, v136
	v_mul_u32_u24_e32 v141, 0x8e, v134
	v_add_u32_e32 v141, v141, v162
	v_mov_b32_dpp v142, v26 quad_perm:[1,0,3,2] row_mask:0xf bank_mask:0xf
	v_perm_b32 v143, v142, v26, v140
	ds_write_b32 v141, v143
	v_mov_b32_dpp v144, v27 quad_perm:[1,0,3,2] row_mask:0xf bank_mask:0xf
	v_perm_b32 v145, v144, v27, v140
	ds_write_b32 v141, v145 offset:288
	v_mov_b32_dpp v146, v28 quad_perm:[1,0,3,2] row_mask:0xf bank_mask:0xf
	v_perm_b32 v147, v146, v28, v140
	ds_write_b32 v141, v147 offset:576
	v_mov_b32_dpp v148, v29 quad_perm:[1,0,3,2] row_mask:0xf bank_mask:0xf
	v_perm_b32 v149, v148, v29, v140
	ds_write_b32 v141, v149 offset:864
	s_waitcnt vmcnt(6)
	v_mov_b32_dpp v142, v22 quad_perm:[1,0,3,2] row_mask:0xf bank_mask:0xf
	v_perm_b32 v143, v142, v22, v140
	ds_write_b32 v141, v143 offset:9216
	v_mov_b32_dpp v144, v23 quad_perm:[1,0,3,2] row_mask:0xf bank_mask:0xf
	v_perm_b32 v145, v144, v23, v140
	ds_write_b32 v141, v145 offset:9504
	v_mov_b32_dpp v146, v24 quad_perm:[1,0,3,2] row_mask:0xf bank_mask:0xf
	v_perm_b32 v147, v146, v24, v140
	ds_write_b32 v141, v147 offset:9792
	v_mov_b32_dpp v148, v25 quad_perm:[1,0,3,2] row_mask:0xf bank_mask:0xf
	v_perm_b32 v149, v148, v25, v140
	ds_write_b32 v141, v149 offset:10080
	s_waitcnt vmcnt(5)
	v_mov_b32_dpp v142, v18 quad_perm:[1,0,3,2] row_mask:0xf bank_mask:0xf
	v_perm_b32 v143, v142, v18, v140
	ds_write_b32 v141, v143 offset:18432
	v_mov_b32_dpp v144, v19 quad_perm:[1,0,3,2] row_mask:0xf bank_mask:0xf
	v_perm_b32 v145, v144, v19, v140
	ds_write_b32 v141, v145 offset:18720
	v_mov_b32_dpp v146, v20 quad_perm:[1,0,3,2] row_mask:0xf bank_mask:0xf
	v_perm_b32 v147, v146, v20, v140
	ds_write_b32 v141, v147 offset:19008
	v_mov_b32_dpp v148, v21 quad_perm:[1,0,3,2] row_mask:0xf bank_mask:0xf
	v_perm_b32 v149, v148, v21, v140
	ds_write_b32 v141, v149 offset:19296
	s_waitcnt vmcnt(4)
	v_mov_b32_dpp v142, v12 quad_perm:[1,0,3,2] row_mask:0xf bank_mask:0xf
	v_perm_b32 v143, v142, v12, v140
	ds_write_b32 v141, v143 offset:27648
	v_mov_b32_dpp v144, v13 quad_perm:[1,0,3,2] row_mask:0xf bank_mask:0xf
	v_perm_b32 v145, v144, v13, v140
	ds_write_b32 v141, v145 offset:27936
	v_mov_b32_dpp v146, v14 quad_perm:[1,0,3,2] row_mask:0xf bank_mask:0xf
	v_perm_b32 v147, v146, v14, v140
	ds_write_b32 v141, v147 offset:28224
	v_mov_b32_dpp v148, v15 quad_perm:[1,0,3,2] row_mask:0xf bank_mask:0xf
	v_perm_b32 v149, v148, v15, v140
	ds_write_b32 v141, v149 offset:28512
	s_waitcnt vmcnt(3)
	v_mov_b32_dpp v142, v8 quad_perm:[1,0,3,2] row_mask:0xf bank_mask:0xf
	v_perm_b32 v143, v142, v8, v140
	ds_write_b32 v141, v143 offset:36864
	v_mov_b32_dpp v144, v9 quad_perm:[1,0,3,2] row_mask:0xf bank_mask:0xf
	v_perm_b32 v145, v144, v9, v140
	ds_write_b32 v141, v145 offset:37152
	v_mov_b32_dpp v146, v10 quad_perm:[1,0,3,2] row_mask:0xf bank_mask:0xf
	v_perm_b32 v147, v146, v10, v140
	ds_write_b32 v141, v147 offset:37440
	v_mov_b32_dpp v148, v11 quad_perm:[1,0,3,2] row_mask:0xf bank_mask:0xf
	v_perm_b32 v149, v148, v11, v140
	ds_write_b32 v141, v149 offset:37728
	s_waitcnt vmcnt(2)
	v_mov_b32_dpp v142, v4 quad_perm:[1,0,3,2] row_mask:0xf bank_mask:0xf
	v_perm_b32 v143, v142, v4, v140
	ds_write_b32 v141, v143 offset:46080
	v_mov_b32_dpp v144, v5 quad_perm:[1,0,3,2] row_mask:0xf bank_mask:0xf
	v_perm_b32 v145, v144, v5, v140
	ds_write_b32 v141, v145 offset:46368
	v_mov_b32_dpp v146, v6 quad_perm:[1,0,3,2] row_mask:0xf bank_mask:0xf
	v_perm_b32 v147, v146, v6, v140
	ds_write_b32 v141, v147 offset:46656
	v_mov_b32_dpp v148, v7 quad_perm:[1,0,3,2] row_mask:0xf bank_mask:0xf
	v_perm_b32 v149, v148, v7, v140
	ds_write_b32 v141, v149 offset:46944
	s_waitcnt vmcnt(1)
	v_mov_b32_dpp v142, v0 quad_perm:[1,0,3,2] row_mask:0xf bank_mask:0xf
	v_perm_b32 v143, v142, v0, v140
	ds_write_b32 v141, v143 offset:55296
	v_mov_b32_dpp v144, v1 quad_perm:[1,0,3,2] row_mask:0xf bank_mask:0xf
	v_perm_b32 v145, v144, v1, v140
	ds_write_b32 v141, v145 offset:55584
	v_mov_b32_dpp v146, v2 quad_perm:[1,0,3,2] row_mask:0xf bank_mask:0xf
	v_perm_b32 v147, v146, v2, v140
	ds_write_b32 v141, v147 offset:55872
	v_mov_b32_dpp v148, v3 quad_perm:[1,0,3,2] row_mask:0xf bank_mask:0xf
	v_perm_b32 v149, v148, v3, v140
	ds_write_b32 v141, v149 offset:56160
	s_waitcnt vmcnt(0)
	v_mov_b32_dpp v142, v98 quad_perm:[1,0,3,2] row_mask:0xf bank_mask:0xf
	v_perm_b32 v143, v142, v98, v140
	ds_write_b32 v141, v143 offset:64512
	v_mov_b32_dpp v144, v99 quad_perm:[1,0,3,2] row_mask:0xf bank_mask:0xf
	v_perm_b32 v145, v144, v99, v140
	ds_write_b32 v141, v145 offset:64800
	v_mov_b32_dpp v146, v100 quad_perm:[1,0,3,2] row_mask:0xf bank_mask:0xf
	v_perm_b32 v147, v146, v100, v140
	ds_write_b32 v141, v147 offset:65088
	v_mov_b32_dpp v148, v101 quad_perm:[1,0,3,2] row_mask:0xf bank_mask:0xf
	v_perm_b32 v149, v148, v101, v140
	ds_write_b32 v141, v149 offset:65376
	v_add_u32_e32 v16, 0, v217
	s_waitcnt lgkmcnt(0)
	s_barrier
; #define LAS __attribute__((address_space(3)))
; __device__ __forceinline__ unsigned pk2(float lo, float hi) { return pg8::cvt_pk_bf16(lo, hi); }
; __device__ __forceinline__ f32x4 mma16(bf16x8 a, bf16x8 b, f32x4 c) { return __builtin_amdgcn_mfma_f32_16x16x32_bf16(a, b, c, 0, 0, 0); }
; #define BSYNC() do { asm volatile("s_waitcnt vmcnt(0) lgkmcnt(0)" ::: "memory"); __syncthreads(); } while (0)
; template <int TY> __device__ __forceinline__ void mc_item(const Params& p, ldsp lds, int item) {
;     ...
;         { f32x4 c0 = (f32x4){0.f, 0.f, 0.f, 0.f}, c1 = c0;
; #pragma unroll
;           for (int ks = 0; ks < DK / 32; ++ks) { const bf16x8 bq = ldfrag(QX, (16 * tt + l15) * PQ + 32 * ks + 8 * q4);
;               c0 = mma16(ldfrag(KTs, (16 * (2 * sp) + l15) * PQ + 32 * ks + 8 * q4), bq, c0);
;               c1 = mma16(ldfrag(KTs, (16 * (2 * sp + 1) + l15) * PQ + 32 * ks + 8 * q4), bq, c1); }
;           const int t = 16 * tt + l15;
;           const int tl = (j == jc) ? t : 4096;
; #pragma unroll
;           for (int jj = 0; jj < 4; ++jj) { if (32 * sp + 4 * q4 + jj > tl) c0[jj] = 0.f; if (32 * sp + 16 + 4 * q4 + jj > tl) c1[jj] = 0.f; }
;           u32x2 w; w.x = pk2(c0[0], c0[1]); w.y = pk2(c0[2], c0[3]); *(LAS u32x2*)(Pm + (size_t)(t * 72 + 32 * sp + 4 * q4) * 2) = w;
;           w.x = pk2(c1[0], c1[1]); w.y = pk2(c1[2], c1[3]); *(LAS u32x2*)(Pm + (size_t)(t * 72 + 32 * sp + 16 + 4 * q4) * 2) = w; }
;         if constexpr (TY == 2) __syncthreads(); else BSYNC();
; #pragma unroll
;         for (int ks = 0; ks < 2; ++ks) { bf16x8 pb[4];
; #pragma unroll
;             for (int tk = 0; tk < 4; ++tk) pb[tk] = ldfrag(Pm, (16 * tk + l15) * 72 + 32 * ks + 8 * q4);
	ds_read_b128 v[0:3], v16 offset:33792
	v_add_u32_e32 v30, 0, v163
	ds_read_b128 v[4:7], v30
	ds_read_b128 v[8:11], v30 offset:64
	ds_read_b128 v[12:15], v16 offset:33856
	s_waitcnt lgkmcnt(2)
	v_mfma_f32_16x16x32_bf16 v[0:3], v[0:3], v[4:7], 0
	v_add_u32_e32 v31, 0, v216
	ds_read_b128 v[18:21], v31 offset:33792
	ds_read_b128 v[22:25], v31 offset:33856
	v_cmp_gt_i32_e32 vcc, v157, v155
	s_waitcnt lgkmcnt(2)
	v_mfma_f32_16x16x32_bf16 v[0:3], v[12:15], v[8:11], v[0:3]
	ds_read_b128 v[12:15], v16 offset:33920
	v_or_b32_e32 v146, 16, v150
	s_cmp_gt_u32 s40, 3
	s_waitcnt lgkmcnt(2)
	v_mfma_f32_16x16x32_bf16 v[4:7], v[18:21], v[4:7], 0
	s_mov_b64 s[0:1], -1
	s_waitcnt lgkmcnt(1)
	v_mfma_f32_16x16x32_bf16 v[4:7], v[22:25], v[8:11], v[4:7]
	ds_read_b128 v[8:11], v30 offset:128
	ds_read_b128 v[18:21], v30 offset:192
	ds_read_b128 v[22:25], v16 offset:33984
	s_waitcnt lgkmcnt(2)
	v_mfma_f32_16x16x32_bf16 v[0:3], v[12:15], v[8:11], v[0:3]
	ds_read_b128 v[12:15], v31 offset:33920
	ds_read_b128 v[26:29], v31 offset:33984
	s_waitcnt lgkmcnt(1)
	v_mfma_f32_16x16x32_bf16 v[4:7], v[12:15], v[8:11], v[4:7]
	ds_read_b128 v[8:11], v16 offset:34048
	v_mfma_f32_16x16x32_bf16 v[0:3], v[22:25], v[18:21], v[0:3]
	s_waitcnt lgkmcnt(1)
	v_mfma_f32_16x16x32_bf16 v[4:7], v[26:29], v[18:21], v[4:7]
	ds_read_b128 v[12:15], v30 offset:256
	ds_read_b128 v[18:21], v30 offset:320
	ds_read_b128 v[22:25], v16 offset:34112
	s_waitcnt lgkmcnt(2)
	v_mfma_f32_16x16x32_bf16 v[0:3], v[8:11], v[12:15], v[0:3]
	ds_read_b128 v[8:11], v31 offset:34048
	ds_read_b128 v[26:29], v31 offset:34112
	s_waitcnt lgkmcnt(1)
	v_mfma_f32_16x16x32_bf16 v[4:7], v[8:11], v[12:15], v[4:7]
	ds_read_b128 v[8:11], v16 offset:34176
	v_mfma_f32_16x16x32_bf16 v[0:3], v[22:25], v[18:21], v[0:3]
	s_waitcnt lgkmcnt(1)
	v_mfma_f32_16x16x32_bf16 v[4:7], v[26:29], v[18:21], v[4:7]
	ds_read_b128 v[12:15], v30 offset:384
	ds_read_b128 v[18:21], v30 offset:448
	ds_read_b128 v[22:25], v16 offset:34240
	v_mad_u32_u24 v16, v146, s9, v154
	s_waitcnt lgkmcnt(2)
	v_mfma_f32_16x16x32_bf16 v[0:3], v[8:11], v[12:15], v[0:3]
	ds_read_b128 v[8:11], v31 offset:34176
	ds_read_b128 v[26:29], v31 offset:34240
	s_waitcnt lgkmcnt(1)
	v_mfma_f32_16x16x32_bf16 v[4:7], v[8:11], v[12:15], v[4:7]
	v_mov_b32_e32 v8, s41
	v_add_u32_e32 v12, v139, v202
	v_mfma_f32_16x16x32_bf16 v[0:3], v[22:25], v[18:21], v[0:3]
	s_waitcnt lgkmcnt(0)
	v_mfma_f32_16x16x32_bf16 v[4:7], v[26:29], v[18:21], v[4:7]
	s_nop 5
	v_cndmask_b32_e32 v9, v0, v8, vcc
	v_cmp_gt_i32_e32 vcc, v215, v155
	s_nop 1
	v_cndmask_b32_e32 v4, v4, v8, vcc
	v_cmp_lt_i32_e32 vcc, v157, v155
	v_or_b32_e32 v8, 2, v157
	s_nop 0
	v_cndmask_b32_e32 v0, v9, v0, vcc
	v_cndmask_b32_e32 v1, 0, v1, vcc
	v_cmp_le_i32_e32 vcc, v214, v155
	v_cvt_pk_bf16_f32 v0, v0, v1
	s_nop 1
	v_cndmask_b32_e32 v5, 0, v5, vcc
	v_cmp_le_i32_e32 vcc, v8, v155
	v_add_u32_e32 v8, v154, v201
	s_nop 0
	v_cndmask_b32_e32 v2, 0, v2, vcc
	v_cmp_le_i32_e32 vcc, v211, v155
	s_nop 1
	v_cndmask_b32_e32 v6, 0, v6, vcc
	v_cmp_le_i32_e32 vcc, v212, v155
	s_nop 1
	v_cndmask_b32_e32 v3, 0, v3, vcc
	v_cvt_pk_bf16_f32 v1, v2, v3
	v_add_u32_e32 v2, 0, v156
	v_cmp_le_i32_e32 vcc, v213, v155
	v_add_u32_e32 v2, 0x22800, v2
	ds_write_b64 v2, v[0:1]
	v_cndmask_b32_e32 v7, 0, v7, vcc
	v_cvt_pk_bf16_f32 v0, v4, v5
	v_cvt_pk_bf16_f32 v1, v6, v7
	ds_write_b64 v2, v[0:1] offset:32
	s_waitcnt lgkmcnt(0)
	s_barrier
	ds_read_b128 v[0:3], v12
	ds_read_b128 v[4:7], v8
	ds_read_b128 v[8:11], v8 offset:64
	ds_read_b128 v[12:15], v12 offset:64
	ds_read_b128 v[22:25], v16
	ds_read_b128 v[26:29], v16 offset:64
	ds_read_b128 v[34:37], v16 offset:2304
	ds_read_b128 v[38:41], v16 offset:2368
	s_waitcnt lgkmcnt(1)
	v_mfma_f32_16x16x32_bf16 v[46:49], v[0:3], v[34:37], v[50:53]
	s_nop 2
	ds_read_b128 v[50:53], v16 offset:4608
	ds_read_b128 v[54:57], v16 offset:4672
	v_add_u32_e32 v16, v139, v160
	v_mfma_f32_16x16x32_bf16 v[18:21], v[0:3], v[4:7], v[62:65]
	v_mfma_f32_16x16x32_bf16 v[30:33], v[0:3], v[22:25], v[58:61]
	s_waitcnt lgkmcnt(1)
	v_mfma_f32_16x16x32_bf16 v[0:3], v[0:3], v[50:53], v[42:45]
	s_nop 2
	ds_read_b128 v[42:45], v16
	ds_read_b128 v[58:61], v16 offset:64
	v_add_u32_e32 v16, v139, v159
	ds_read_b128 v[62:65], v16
	ds_read_b128 v[122:125], v16 offset:64
	v_add_u32_e32 v16, v139, v158
	s_waitcnt lgkmcnt(1)
	v_mfma_f32_16x16x32_bf16 v[126:129], v[62:65], v[4:7], v[82:85]
	v_mfma_f32_16x16x32_bf16 v[130:133], v[62:65], v[22:25], v[86:89]
	v_mfma_f32_16x16x32_bf16 v[134:137], v[62:65], v[34:37], v[90:93]
	v_mfma_f32_16x16x32_bf16 v[140:143], v[62:65], v[50:53], v[94:97]
	ds_read_b128 v[62:65], v16
	ds_read_b128 v[154:157], v16 offset:64
	s_waitcnt lgkmcnt(0)
	s_barrier
; __device__ __forceinline__ f32x4 mma16(bf16x8 a, bf16x8 b, f32x4 c) { return __builtin_amdgcn_mfma_f32_16x16x32_bf16(a, b, c, 0, 0, 0); }
; #define BSYNC() do { asm volatile("s_waitcnt vmcnt(0) lgkmcnt(0)" ::: "memory"); __syncthreads(); } while (0)
; template <int TY> __device__ __forceinline__ void mc_item(const Params& p, ldsp lds, int item) {
;     ...
;         for (int ks = 0; ks < 2; ++ks) { bf16x8 pb[4];
; #pragma unroll
;             for (int tk = 0; tk < 4; ++tk) pb[tk] = ldfrag(Pm, (16 * tk + l15) * 72 + 32 * ks + 8 * q4);
; #pragma unroll
;             for (int ei = 0; ei < ET; ++ei) { const bf16x8 va = ldfrag(VTs, (16 * (wave * ET + ei) + l15) * 72 + 32 * ks + 8 * q4);
; #pragma unroll
;                 for (int tk = 0; tk < 4; ++tk) acc[ei][tk] = mma16(va, pb[tk], acc[ei][tk]); } }
;         if constexpr (TY == 2) __syncthreads(); else BSYNC(); }
;     if ((TY == 2 ? sc : c) != 0) { const bf16_t* STp = (TY == 2) ? (const bf16_t*)(p.ws + WS_ST) + ((size_t)bh * 8 + sc) * 512 * 256
;                                     : (const bf16_t*)(p.ws + WS_ST + (TY ? ST_HGRN : 0)) + ((size_t)bh * 32 + c) * 128 * DK;
;       ldsp QS = (TY == 2) ? QX : QH2;
;       bf16x8 sa[ET], sn[ET];
; #pragma unroll
;       for (int ei = 0; ei < ET; ++ei) sa[ei] = *(const bf16x8*)(STp + (size_t)(16 * (wave * ET + ei) + l15) * DK + 8 * q4);
; #pragma unroll 1
;       for (int ks = 0; ks < DK / 32; ++ks) { bf16x8 qb[4];
;           const int kn = (ks + 1 < DK / 32) ? ks + 1 : ks;
; #pragma unroll
;           for (int ei = 0; ei < ET; ++ei) sn[ei] = *(const bf16x8*)(STp + (size_t)(16 * (wave * ET + ei) + l15) * DK + 32 * kn + 8 * q4);
; #pragma unroll
;           for (int tk = 0; tk < 4; ++tk) qb[tk] = ldfrag(QS, (16 * tk + l15) * PQ + 32 * ks + 8 * q4);
; #pragma unroll
;           for (int ei = 0; ei < ET; ++ei) {
; #pragma unroll
;               for (int tk = 0; tk < 4; ++tk) acc[ei][tk] = mma16(sa[ei], qb[tk], acc[ei][tk]); }
; #pragma unroll
;           for (int ei = 0; ei < ET; ++ei) sa[ei] = sn[ei]; } }
	v_mfma_f32_16x16x32_bf16 v[66:69], v[42:45], v[4:7], v[66:69]
	v_mfma_f32_16x16x32_bf16 v[98:101], v[42:45], v[22:25], v[70:73]
	v_mfma_f32_16x16x32_bf16 v[118:121], v[42:45], v[34:37], v[74:77]
	v_mfma_f32_16x16x32_bf16 v[42:45], v[42:45], v[50:53], v[78:81]
	v_mfma_f32_16x16x32_bf16 v[4:7], v[62:65], v[4:7], v[102:105]
	v_mfma_f32_16x16x32_bf16 v[22:25], v[62:65], v[22:25], v[106:109]
	v_mfma_f32_16x16x32_bf16 v[34:37], v[62:65], v[34:37], v[110:113]
	v_mfma_f32_16x16x32_bf16 v[50:53], v[62:65], v[50:53], v[114:117]
	v_mfma_f32_16x16x32_bf16 v[62:65], v[12:15], v[8:11], v[18:21]
	v_mfma_f32_16x16x32_bf16 v[70:73], v[12:15], v[26:29], v[30:33]
	v_mfma_f32_16x16x32_bf16 v[74:77], v[12:15], v[38:41], v[46:49]
	v_mfma_f32_16x16x32_bf16 v[110:113], v[12:15], v[54:57], v[0:3]
	v_mfma_f32_16x16x32_bf16 v[78:81], v[58:61], v[8:11], v[66:69]
	v_mfma_f32_16x16x32_bf16 v[82:85], v[58:61], v[26:29], v[98:101]
	v_mfma_f32_16x16x32_bf16 v[86:89], v[58:61], v[38:41], v[118:121]
	v_mfma_f32_16x16x32_bf16 v[90:93], v[58:61], v[54:57], v[42:45]
	v_mfma_f32_16x16x32_bf16 v[94:97], v[122:125], v[8:11], v[126:129]
	v_mfma_f32_16x16x32_bf16 v[98:101], v[122:125], v[26:29], v[130:133]
	v_mfma_f32_16x16x32_bf16 v[102:105], v[122:125], v[38:41], v[134:137]
	v_mfma_f32_16x16x32_bf16 v[106:109], v[122:125], v[54:57], v[140:143]
	v_mfma_f32_16x16x32_bf16 v[114:117], v[154:157], v[8:11], v[4:7]
	v_mfma_f32_16x16x32_bf16 v[118:121], v[154:157], v[26:29], v[22:25]
	v_mfma_f32_16x16x32_bf16 v[122:125], v[154:157], v[38:41], v[34:37]
	v_mfma_f32_16x16x32_bf16 v[126:129], v[154:157], v[54:57], v[50:53]
	s_cbranch_scc0 .LBB0_887
	s_ashr_i32 s9, s8, 31
	s_lshl_b64 s[0:1], s[8:9], 21
	v_readlane_b32 s8, v254, 9
	v_readlane_b32 s9, v254, 10
	s_add_u32 s0, s8, s0
	s_addc_u32 s1, s9, s1
	s_lshl_b32 s8, s40, 16
	s_and_b32 s8, s8, 0x1c0000
	s_add_u32 s0, s0, s8
	s_addc_u32 s1, s1, 0
	s_and_b32 s9, s60, 0xffffffc0
	v_or_b32_e32 v0, s9, v150
	v_or_b32_e32 v2, 16, v0
	v_ashrrev_i32_e32 v1, 31, v0
	v_ashrrev_i32_e32 v3, 31, v2
	v_lshlrev_b32_e32 v16, 1, v138
	v_lshlrev_b64 v[132:133], 9, v[0:1]
	v_lshlrev_b64 v[138:139], 9, v[2:3]
	v_or_b32_e32 v2, 32, v0
	v_or_b32_e32 v0, 48, v0
	v_ashrrev_i32_e32 v1, 31, v0
	v_ashrrev_i32_e32 v3, 31, v2
	v_lshlrev_b64 v[142:143], 9, v[0:1]
	v_mul_u32_u24_e32 v0, 0x210, v150
	v_lshl_add_u64 v[130:131], s[0:1], 0, v[16:17]
	v_lshlrev_b64 v[140:141], 9, v[2:3]
	v_add3_u32 v16, v0, v153, 0
	v_lshl_add_u64 v[202:203], v[130:131], 0, v[132:133]
	v_lshl_add_u64 v[210:211], v[130:131], 0, v[138:139]
	v_lshl_add_u64 v[250:251], v[130:131], 0, v[140:141]
	v_lshl_add_u64 v[148:149], v[130:131], 0, v[142:143]
	global_load_dwordx4 v[186:189], v[202:203], off
	global_load_dwordx4 v[190:193], v[210:211], off
	global_load_dwordx4 v[194:197], v[250:251], off
	global_load_dwordx4 v[198:201], v[148:149], off
	global_load_dwordx4 v[206:209], v[202:203], off offset:64
	global_load_dwordx4 v[246:249], v[210:211], off offset:64
	global_load_dwordx4 v[134:137], v[250:251], off offset:64
	global_load_dwordx4 v[154:157], v[148:149], off offset:64
	global_load_dwordx4 v[172:175], v[202:203], off offset:128
	global_load_dwordx4 v[176:179], v[210:211], off offset:128
	global_load_dwordx4 v[180:183], v[250:251], off offset:128
	global_load_dwordx4 v[166:169], v[148:149], off offset:128
	ds_read_b128 v[214:217], v16
	ds_read_b128 v[218:221], v16 offset:8448
	ds_read_b128 v[222:225], v16 offset:16896
	ds_read_b128 v[226:229], v16 offset:25344
	v_mov_b64_e32 v[50:51], v[110:111]
	v_mov_b64_e32 v[54:55], v[74:75]
	v_mov_b64_e32 v[58:59], v[70:71]
	v_mov_b64_e32 v[68:69], v[64:65]
	v_mov_b64_e32 v[46:47], v[78:79]
	v_mov_b64_e32 v[42:43], v[82:83]
	v_mov_b64_e32 v[38:39], v[86:87]
	v_mov_b64_e32 v[34:35], v[90:91]
	v_mov_b64_e32 v[30:31], v[94:95]
	v_mov_b64_e32 v[26:27], v[98:99]
	v_mov_b64_e32 v[22:23], v[102:103]
	v_mov_b64_e32 v[18:19], v[106:107]
	v_mov_b64_e32 v[12:13], v[114:115]
	v_mov_b64_e32 v[8:9], v[118:119]
	v_mov_b64_e32 v[4:5], v[122:123]
	v_mov_b64_e32 v[0:1], v[126:127]
	s_mov_b32 s0, 32
	v_mov_b64_e32 v[52:53], v[112:113]
	v_mov_b64_e32 v[56:57], v[76:77]
	v_mov_b64_e32 v[60:61], v[72:73]
	v_mov_b64_e32 v[66:67], v[62:63]
	v_mov_b64_e32 v[144:145], v[130:131]
	v_mov_b64_e32 v[48:49], v[80:81]
	v_mov_b64_e32 v[44:45], v[84:85]
	v_mov_b64_e32 v[40:41], v[88:89]
	v_mov_b64_e32 v[36:37], v[92:93]
	v_mov_b64_e32 v[32:33], v[96:97]
	v_mov_b64_e32 v[28:29], v[100:101]
	v_mov_b64_e32 v[24:25], v[104:105]
	v_mov_b64_e32 v[20:21], v[108:109]
	v_mov_b64_e32 v[14:15], v[116:117]
	v_mov_b64_e32 v[10:11], v[120:121]
	v_mov_b64_e32 v[6:7], v[124:125]
	v_mov_b64_e32 v[2:3], v[128:129]
